# attention unit epilogue: 32 partner LDS reads issued 14 ahead with counted lgkmcnt and the 16 sub-LN weight loads issued up front into dead registers (on top of gate epilogue)
# baseline (speedup 1.0000x reference)
.LBB0_239:
	v_readlane_b32 s48, v255, 37
	s_andn2_b64 vcc, exec, s[8:9]
	v_readlane_b32 s49, v255, 38
	s_waitcnt lgkmcnt(0)
	s_barrier
	s_cbranch_vccnz .LBB0_204
	v_readlane_b32 s8, v255, 45
	v_readlane_b32 s9, v255, 46
	v_mov_b32_e32 v66, v48
	s_nop 3
	global_load_dword v67, v129, s[8:9]
	s_lshl_b32 s8, s40, 14
	s_add_i32 s8, s8, 0
	v_lshl_add_u32 v71, v183, 2, s8
	ds_read2st64_b32 v[80:81], v71 offset1:1
	ds_read2st64_b32 v[82:83], v71 offset0:2 offset1:3
	ds_read2st64_b32 v[84:85], v71 offset0:4 offset1:5
	ds_read2st64_b32 v[86:87], v71 offset0:6 offset1:7
	ds_read2st64_b32 v[88:89], v71 offset0:8 offset1:9
	ds_read2st64_b32 v[90:91], v71 offset0:10 offset1:11
	ds_read2st64_b32 v[92:93], v71 offset0:12 offset1:13
	ds_read2st64_b32 v[94:95], v71 offset0:14 offset1:15
	ds_read2st64_b32 v[96:97], v71 offset0:16 offset1:17
	ds_read2st64_b32 v[98:99], v71 offset0:18 offset1:19
	ds_read2st64_b32 v[100:101], v71 offset0:20 offset1:21
	ds_read2st64_b32 v[102:103], v71 offset0:22 offset1:23
	ds_read2st64_b32 v[104:105], v71 offset0:24 offset1:25
	ds_read2st64_b32 v[106:107], v71 offset0:26 offset1:27
	s_load_dwordx2 s[8:9], s[4:5], 0x48
	s_waitcnt lgkmcnt(0)
	v_mov_b32_e32 v65, v80
	s_add_u32 s8, s8, s94
	s_addc_u32 s9, s9, s95
	global_load_dwordx4 v[146:149], v128, s[8:9]
	global_load_dwordx4 v[150:153], v128, s[8:9] offset:32
	global_load_dwordx4 v[154:157], v128, s[8:9] offset:64
	global_load_dwordx4 v[158:161], v128, s[8:9] offset:96
	global_load_dwordx4 v[238:241], v128, s[8:9] offset:128
	global_load_dwordx4 v[242:245], v128, s[8:9] offset:160
	global_load_dwordx4 v[246:249], v128, s[8:9] offset:192
	global_load_dwordx4 v[250:253], v128, s[8:9] offset:224
	global_load_dwordx4 v[210:213], v128, s[8:9] offset:256
	global_load_dwordx4 v[214:217], v128, s[8:9] offset:288
	global_load_dwordx4 v[218:221], v128, s[8:9] offset:320
	global_load_dwordx4 v[222:225], v128, s[8:9] offset:352
	global_load_dwordx4 v[226:229], v128, s[8:9] offset:384
	global_load_dwordx4 v[230:233], v128, s[8:9] offset:416
	global_load_dwordx4 v[234:237], v128, s[8:9] offset:448
	global_load_dwordx4 v[184:187], v128, s[8:9] offset:480
	s_waitcnt vmcnt(16)
	v_pk_mul_f32 v[72:73], v[66:67], v[64:65]
	v_mov_b32_e32 v66, v49
	v_mov_b32_e32 v65, v81
	v_pk_mul_f32 v[68:69], v[66:67], v[64:65]
	v_mov_b32_e32 v66, v50
	v_sub_f32_e32 v49, v68, v69
	ds_read2st64_b32 v[108:109], v71 offset0:28 offset1:29
	v_sub_f32_e32 v48, v72, v73
	s_waitcnt lgkmcnt(13)
	v_mov_b32_e32 v65, v82
	v_pk_mul_f32 v[72:73], v[66:67], v[64:65]
	v_mov_b32_e32 v66, v51
	v_mov_b32_e32 v65, v83
	v_pk_mul_f32 v[68:69], v[66:67], v[64:65]
	v_mov_b32_e32 v66, v52
	v_sub_f32_e32 v51, v68, v69
	ds_read2st64_b32 v[110:111], v71 offset0:30 offset1:31
	v_sub_f32_e32 v50, v72, v73
	s_waitcnt lgkmcnt(13)
	v_mov_b32_e32 v65, v84
	v_pk_mul_f32 v[72:73], v[66:67], v[64:65]
	v_mov_b32_e32 v66, v53
	v_mov_b32_e32 v65, v85
	v_pk_mul_f32 v[68:69], v[66:67], v[64:65]
	v_mov_b32_e32 v66, v54
	v_sub_f32_e32 v53, v68, v69
	ds_read2st64_b32 v[112:113], v71 offset0:32 offset1:33
	v_sub_f32_e32 v52, v72, v73
	s_waitcnt lgkmcnt(13)
	v_mov_b32_e32 v65, v86
	v_pk_mul_f32 v[72:73], v[66:67], v[64:65]
	v_mov_b32_e32 v66, v55
	v_mov_b32_e32 v65, v87
	v_pk_mul_f32 v[68:69], v[66:67], v[64:65]
	v_mov_b32_e32 v66, v56
	v_sub_f32_e32 v55, v68, v69
	ds_read2st64_b32 v[114:115], v71 offset0:34 offset1:35
	v_sub_f32_e32 v54, v72, v73
	s_waitcnt lgkmcnt(13)
	v_mov_b32_e32 v65, v88
	v_pk_mul_f32 v[72:73], v[66:67], v[64:65]
	v_mov_b32_e32 v66, v57
	v_mov_b32_e32 v65, v89
	v_pk_mul_f32 v[68:69], v[66:67], v[64:65]
	v_mov_b32_e32 v66, v58
	v_sub_f32_e32 v57, v68, v69
	ds_read2st64_b32 v[116:117], v71 offset0:36 offset1:37
	v_sub_f32_e32 v56, v72, v73
	s_waitcnt lgkmcnt(13)
	v_mov_b32_e32 v65, v90
	v_pk_mul_f32 v[72:73], v[66:67], v[64:65]
	v_mov_b32_e32 v66, v59
	v_mov_b32_e32 v65, v91
	v_pk_mul_f32 v[68:69], v[66:67], v[64:65]
	v_mov_b32_e32 v66, v60
	v_sub_f32_e32 v59, v68, v69
	ds_read2st64_b32 v[118:119], v71 offset0:38 offset1:39
	v_sub_f32_e32 v58, v72, v73
	s_waitcnt lgkmcnt(13)
	v_mov_b32_e32 v65, v92
	v_pk_mul_f32 v[72:73], v[66:67], v[64:65]
	v_mov_b32_e32 v66, v61
	v_mov_b32_e32 v65, v93
	v_pk_mul_f32 v[68:69], v[66:67], v[64:65]
	v_mov_b32_e32 v66, v62
	v_sub_f32_e32 v61, v68, v69
	ds_read2st64_b32 v[120:121], v71 offset0:40 offset1:41
	v_sub_f32_e32 v60, v72, v73
	s_waitcnt lgkmcnt(13)
	v_mov_b32_e32 v65, v94
	v_pk_mul_f32 v[72:73], v[66:67], v[64:65]
	v_mov_b32_e32 v66, v63
	v_sub_f32_e32 v62, v72, v73
	ds_read2st64_b32 v[122:123], v71 offset0:42 offset1:43
	v_mov_b32_e32 v65, v95
	v_pk_mul_f32 v[68:69], v[66:67], v[64:65]
	v_mov_b32_e32 v66, v32
	v_sub_f32_e32 v63, v68, v69
	s_waitcnt lgkmcnt(13)
	v_mov_b32_e32 v65, v96
	v_pk_mul_f32 v[68:69], v[66:67], v[64:65]
	v_mov_b32_e32 v66, v33
	v_mov_b32_e32 v65, v97
	v_pk_mul_f32 v[32:33], v[66:67], v[64:65]
	v_sub_f32_e32 v69, v68, v69
	v_sub_f32_e32 v68, v32, v33
	ds_read2st64_b32 v[124:125], v71 offset0:44 offset1:45
	v_mov_b32_e32 v66, v34
	s_waitcnt lgkmcnt(13)
	v_mov_b32_e32 v65, v98
	v_pk_mul_f32 v[72:73], v[66:67], v[64:65]
	v_mov_b32_e32 v66, v35
	v_mov_b32_e32 v65, v99
	v_pk_mul_f32 v[32:33], v[66:67], v[64:65]
	v_mov_b32_e32 v66, v36
	v_sub_f32_e32 v34, v32, v33
	ds_read2st64_b32 v[126:127], v71 offset0:46 offset1:47
	v_sub_f32_e32 v70, v72, v73
	s_waitcnt lgkmcnt(13)
	v_mov_b32_e32 v65, v100
	v_pk_mul_f32 v[72:73], v[66:67], v[64:65]
	v_mov_b32_e32 v66, v37
	v_mov_b32_e32 v65, v101
	v_pk_mul_f32 v[32:33], v[66:67], v[64:65]
	v_mov_b32_e32 v66, v38
	v_sub_f32_e32 v35, v32, v33
	ds_read2st64_b32 v[130:131], v71 offset0:48 offset1:49
	v_sub_f32_e32 v36, v72, v73
	s_waitcnt lgkmcnt(13)
	v_mov_b32_e32 v65, v102
	v_pk_mul_f32 v[72:73], v[66:67], v[64:65]
	v_mov_b32_e32 v66, v39
	v_sub_f32_e32 v38, v72, v73
	ds_read2st64_b32 v[132:133], v71 offset0:50 offset1:51
	v_mov_b32_e32 v65, v103
	v_pk_mul_f32 v[32:33], v[66:67], v[64:65]
	v_mov_b32_e32 v66, v40
	v_sub_f32_e32 v37, v32, v33
	s_waitcnt lgkmcnt(13)
	v_mov_b32_e32 v65, v104
	v_pk_mul_f32 v[32:33], v[66:67], v[64:65]
	v_mov_b32_e32 v66, v41
	v_mov_b32_e32 v65, v105
	v_pk_mul_f32 v[40:41], v[66:67], v[64:65]
	v_sub_f32_e32 v33, v32, v33
	v_sub_f32_e32 v32, v40, v41
	ds_read2st64_b32 v[134:135], v71 offset0:52 offset1:53
	v_mov_b32_e32 v66, v42
	s_waitcnt lgkmcnt(13)
	v_mov_b32_e32 v65, v106
	v_pk_mul_f32 v[72:73], v[66:67], v[64:65]
	v_mov_b32_e32 v66, v43
	v_mov_b32_e32 v65, v107
	v_pk_mul_f32 v[42:43], v[66:67], v[64:65]
	v_mov_b32_e32 v66, v44
	v_sub_f32_e32 v39, v42, v43
	ds_read2st64_b32 v[136:137], v71 offset0:54 offset1:55
	v_sub_f32_e32 v40, v72, v73
	s_waitcnt lgkmcnt(13)
	v_mov_b32_e32 v65, v108
	v_pk_mul_f32 v[72:73], v[66:67], v[64:65]
	v_mov_b32_e32 v66, v45
	v_mov_b32_e32 v65, v109
	v_pk_mul_f32 v[44:45], v[66:67], v[64:65]
	v_mov_b32_e32 v66, v46
	v_sub_f32_e32 v41, v44, v45
	ds_read2st64_b32 v[138:139], v71 offset0:56 offset1:57
	v_sub_f32_e32 v42, v72, v73
	s_waitcnt lgkmcnt(13)
	v_mov_b32_e32 v65, v110
	v_pk_mul_f32 v[72:73], v[66:67], v[64:65]
	v_mov_b32_e32 v66, v47
	v_sub_f32_e32 v46, v72, v73
	ds_read2st64_b32 v[140:141], v71 offset0:58 offset1:59
	v_mov_b32_e32 v65, v111
	v_pk_mul_f32 v[44:45], v[66:67], v[64:65]
	v_mov_b32_e32 v66, v16
	v_sub_f32_e32 v44, v44, v45
	s_waitcnt lgkmcnt(13)
	v_mov_b32_e32 v65, v112
	v_pk_mul_f32 v[74:75], v[66:67], v[64:65]
	v_mov_b32_e32 v66, v17
	v_mov_b32_e32 v65, v113
	v_pk_mul_f32 v[16:17], v[66:67], v[64:65]
	v_mov_b32_e32 v66, v18
	v_sub_f32_e32 v43, v16, v17
	ds_read2st64_b32 v[142:143], v71 offset0:60 offset1:61
	v_sub_f32_e32 v45, v74, v75
	s_waitcnt lgkmcnt(13)
	v_mov_b32_e32 v65, v114
	v_pk_mul_f32 v[72:73], v[66:67], v[64:65]
	v_mov_b32_e32 v66, v19
	v_mov_b32_e32 v65, v115
	v_pk_mul_f32 v[16:17], v[66:67], v[64:65]
	v_mov_b32_e32 v66, v20
	v_sub_f32_e32 v18, v16, v17
	ds_read2st64_b32 v[144:145], v71 offset0:62 offset1:63
	v_sub_f32_e32 v47, v72, v73
	s_waitcnt lgkmcnt(13)
	v_mov_b32_e32 v65, v116
	v_pk_mul_f32 v[72:73], v[66:67], v[64:65]
	v_mov_b32_e32 v66, v21
	v_mov_b32_e32 v65, v117
	v_pk_mul_f32 v[16:17], v[66:67], v[64:65]
	v_mov_b32_e32 v66, v22
	v_sub_f32_e32 v19, v16, v17
	v_sub_f32_e32 v20, v72, v73
	s_waitcnt lgkmcnt(12)
	v_mov_b32_e32 v65, v118
	v_pk_mul_f32 v[72:73], v[66:67], v[64:65]
	v_mov_b32_e32 v66, v23
	v_mov_b32_e32 v65, v119
	v_pk_mul_f32 v[16:17], v[66:67], v[64:65]
	v_mov_b32_e32 v66, v24
	v_sub_f32_e32 v23, v16, v17
	v_sub_f32_e32 v72, v72, v73
	s_waitcnt lgkmcnt(11)
	v_mov_b32_e32 v65, v120
	v_pk_mul_f32 v[74:75], v[66:67], v[64:65]
	v_mov_b32_e32 v66, v25
	v_mov_b32_e32 v65, v121
	v_pk_mul_f32 v[16:17], v[66:67], v[64:65]
	v_mov_b32_e32 v66, v26
	v_sub_f32_e32 v21, v16, v17
	v_sub_f32_e32 v22, v74, v75
	s_waitcnt lgkmcnt(10)
	v_mov_b32_e32 v65, v122
	v_pk_mul_f32 v[24:25], v[66:67], v[64:65]
	v_mov_b32_e32 v66, v27
	v_mov_b32_e32 v65, v123
	v_pk_mul_f32 v[16:17], v[66:67], v[64:65]
	v_sub_f32_e32 v25, v24, v25
	v_sub_f32_e32 v24, v16, v17
	v_mov_b32_e32 v66, v28
	s_waitcnt lgkmcnt(9)
	v_mov_b32_e32 v65, v124
	v_pk_mul_f32 v[26:27], v[66:67], v[64:65]
	v_mov_b32_e32 v66, v29
	v_mov_b32_e32 v65, v125
	v_pk_mul_f32 v[16:17], v[66:67], v[64:65]
	v_sub_f32_e32 v27, v26, v27
	v_sub_f32_e32 v26, v16, v17
	v_mov_b32_e32 v66, v30
	s_waitcnt lgkmcnt(8)
	v_mov_b32_e32 v65, v126
	v_pk_mul_f32 v[28:29], v[66:67], v[64:65]
	v_mov_b32_e32 v66, v31
	v_mov_b32_e32 v65, v127
	v_pk_mul_f32 v[16:17], v[66:67], v[64:65]
	v_mov_b32_e32 v66, v0
	v_sub_f32_e32 v30, v16, v17
	v_sub_f32_e32 v73, v28, v29
	s_waitcnt lgkmcnt(7)
	v_mov_b32_e32 v65, v130
	v_pk_mul_f32 v[28:29], v[66:67], v[64:65]
	v_mov_b32_e32 v66, v1
	v_mov_b32_e32 v65, v131
	v_pk_mul_f32 v[0:1], v[66:67], v[64:65]
	v_sub_f32_e32 v29, v28, v29
	v_sub_f32_e32 v28, v0, v1
	v_mov_b32_e32 v66, v2
	s_waitcnt lgkmcnt(6)
	v_mov_b32_e32 v65, v132
	v_pk_mul_f32 v[16:17], v[66:67], v[64:65]
	v_mov_b32_e32 v66, v3
	v_mov_b32_e32 v65, v133
	v_pk_mul_f32 v[0:1], v[66:67], v[64:65]
	v_mov_b32_e32 v66, v4
	v_sub_f32_e32 v31, v0, v1
	v_sub_f32_e32 v74, v16, v17
	s_waitcnt lgkmcnt(5)
	v_mov_b32_e32 v65, v134
	v_pk_mul_f32 v[2:3], v[66:67], v[64:65]
	v_mov_b32_e32 v66, v5
	v_mov_b32_e32 v65, v135
	v_pk_mul_f32 v[0:1], v[66:67], v[64:65]
	v_mov_b32_e32 v66, v6
	v_sub_f32_e32 v75, v0, v1
	v_sub_f32_e32 v76, v2, v3
	s_waitcnt lgkmcnt(4)
	v_mov_b32_e32 v65, v136
	v_pk_mul_f32 v[2:3], v[66:67], v[64:65]
	v_mov_b32_e32 v66, v7
	v_mov_b32_e32 v65, v137
	v_pk_mul_f32 v[0:1], v[66:67], v[64:65]
	v_mov_b32_e32 v4, v2
	v_mov_b32_e32 v5, v0
	v_mov_b32_e32 v0, v3
	v_mov_b32_e32 v66, v8
	v_pk_add_f32 v[6:7], v[4:5], v[0:1] neg_lo:[0,1] neg_hi:[0,1]
	s_waitcnt lgkmcnt(3)
	v_mov_b32_e32 v65, v138
	v_pk_mul_f32 v[4:5], v[66:67], v[64:65]
	v_mov_b32_e32 v66, v9
	v_mov_b32_e32 v65, v139
	v_pk_mul_f32 v[2:3], v[66:67], v[64:65]
	v_mov_b32_e32 v8, v4
	v_mov_b32_e32 v9, v2
	v_mov_b32_e32 v2, v5
	v_pk_add_f32 v[4:5], v[8:9], v[2:3] neg_lo:[0,1] neg_hi:[0,1]
	v_mov_b32_e32 v66, v10
	v_pk_mul_f32 v[0:1], v[6:7], v[6:7]
	v_pk_mul_f32 v[2:3], v[4:5], v[4:5]
	s_waitcnt lgkmcnt(2)
	v_mov_b32_e32 v65, v140
	v_pk_mul_f32 v[16:17], v[66:67], v[64:65]
	v_mov_b32_e32 v66, v11
	v_mov_b32_e32 v65, v141
	v_pk_mul_f32 v[8:9], v[66:67], v[64:65]
	v_mov_b32_e32 v10, v16
	v_mov_b32_e32 v11, v8
	v_mov_b32_e32 v8, v17
	v_pk_add_f32 v[8:9], v[10:11], v[8:9] neg_lo:[0,1] neg_hi:[0,1]
	v_mov_b32_e32 v66, v12
	v_pk_mul_f32 v[16:17], v[8:9], v[8:9]
	s_waitcnt lgkmcnt(1)
	v_mov_b32_e32 v65, v142
	v_pk_mul_f32 v[78:79], v[66:67], v[64:65]
	v_mov_b32_e32 v66, v13
	v_mov_b32_e32 v65, v143
	v_pk_mul_f32 v[10:11], v[66:67], v[64:65]
	v_mov_b32_e32 v12, v78
	v_mov_b32_e32 v13, v10
	v_mov_b32_e32 v10, v79
	v_pk_add_f32 v[10:11], v[12:13], v[10:11] neg_lo:[0,1] neg_hi:[0,1]
	v_mov_b32_e32 v66, v67
	v_pk_mul_f32 v[78:79], v[10:11], v[10:11]
	s_waitcnt lgkmcnt(0)
	v_pk_mul_f32 v[12:13], v[66:67], v[144:145] op_sel_hi:[0,1]
	v_pk_fma_f32 v[12:13], v[14:15], v[64:65], v[12:13] op_sel_hi:[1,0,1] neg_lo:[0,0,1] neg_hi:[0,0,1]
	v_mul_f32_e32 v64, v48, v48
	v_fmac_f32_e32 v64, v49, v49
	v_fmac_f32_e32 v64, v50, v50
	v_fmac_f32_e32 v64, v51, v51
	v_fmac_f32_e32 v64, v52, v52
	v_fmac_f32_e32 v64, v53, v53
	v_fmac_f32_e32 v64, v54, v54
	v_fmac_f32_e32 v64, v55, v55
	v_fmac_f32_e32 v64, v56, v56
	v_fmac_f32_e32 v64, v57, v57
	v_fmac_f32_e32 v64, v58, v58
	v_fmac_f32_e32 v64, v59, v59
	v_fmac_f32_e32 v64, v60, v60
	v_fmac_f32_e32 v64, v61, v61
	v_fmac_f32_e32 v64, v62, v62
	v_fmac_f32_e32 v64, v63, v63
	v_fmac_f32_e32 v64, v69, v69
	v_fmac_f32_e32 v64, v68, v68
	v_fmac_f32_e32 v64, v70, v70
	v_fmac_f32_e32 v64, v34, v34
	v_fmac_f32_e32 v64, v36, v36
	v_fmac_f32_e32 v64, v35, v35
	v_fmac_f32_e32 v64, v38, v38
	v_fmac_f32_e32 v64, v37, v37
	v_fmac_f32_e32 v64, v33, v33
	v_fmac_f32_e32 v64, v32, v32
	v_fmac_f32_e32 v64, v40, v40
	v_fmac_f32_e32 v64, v39, v39
	v_fmac_f32_e32 v64, v42, v42
	v_fmac_f32_e32 v64, v41, v41
	v_fmac_f32_e32 v64, v46, v46
	v_fmac_f32_e32 v64, v44, v44
	v_fmac_f32_e32 v64, v45, v45
	v_fmac_f32_e32 v64, v43, v43
	v_fmac_f32_e32 v64, v47, v47
	v_fmac_f32_e32 v64, v18, v18
	v_fmac_f32_e32 v64, v20, v20
	v_fmac_f32_e32 v64, v19, v19
	v_fmac_f32_e32 v64, v72, v72
	v_fmac_f32_e32 v64, v23, v23
	v_fmac_f32_e32 v64, v22, v22
	v_fmac_f32_e32 v64, v21, v21
	v_fmac_f32_e32 v64, v25, v25
	v_fmac_f32_e32 v64, v24, v24
	v_fmac_f32_e32 v64, v27, v27
	v_fmac_f32_e32 v64, v26, v26
	v_fmac_f32_e32 v64, v73, v73
	v_fmac_f32_e32 v64, v30, v30
	v_fmac_f32_e32 v64, v29, v29
	v_fmac_f32_e32 v64, v28, v28
	v_fmac_f32_e32 v64, v74, v74
	v_fmac_f32_e32 v64, v31, v31
	v_fmac_f32_e32 v64, v76, v76
	v_fmac_f32_e32 v64, v75, v75
	v_add_f32_e32 v0, v64, v0
	v_add_f32_e32 v0, v0, v1
	v_add_f32_e32 v0, v0, v2
	v_add_f32_e32 v0, v0, v3
	v_add_f32_e32 v0, v0, v16
	v_add_f32_e32 v0, v0, v17
	v_add_f32_e32 v0, v0, v78
	v_pk_mul_f32 v[14:15], v[12:13], v[12:13]
	v_add_f32_e32 v0, v0, v79
	v_add_f32_e32 v0, v0, v14
	v_add_f32_e32 v0, v0, v15
	ds_bpermute_b32 v1, v179, v0
	s_waitcnt lgkmcnt(0)
	v_add_f32_e32 v0, v0, v1
	v_fmamk_f32 v0, v0, 0x3c000000, v162
	v_cmp_gt_f32_e32 vcc, s75, v0
	v_mul_f32_e32 v1, 0x4b800000, v0
	s_nop 0
	v_cndmask_b32_e32 v0, v0, v1, vcc
	v_rsq_f32_e32 v0, v0
	s_nop 0
	v_mul_f32_e32 v1, 0x45800000, v0
	v_cndmask_b32_e32 v0, v0, v1, vcc
	v_mul_f32_e32 v16, v208, v0
	v_lshlrev_b64 v[0:1], 12, v[176:177]
	v_lshl_add_u64 v[14:15], s[16:17], 0, v[0:1]
	v_mul_f32_e32 v17, v48, v16
	s_waitcnt vmcnt(15)
	v_mul_f32_e32 v0, v146, v17
	v_mul_f32_e32 v17, v49, v16
	v_mul_f32_e32 v1, v147, v17
	v_cvt_pk_bf16_f32 v48, v0, v1
	v_mul_f32_e32 v0, v50, v16
	v_mul_f32_e32 v1, v51, v16
	v_mul_f32_e32 v0, v148, v0
	v_mul_f32_e32 v1, v149, v1
	v_cvt_pk_bf16_f32 v49, v0, v1
	v_lshlrev_b32_e32 v0, 3, v182
	v_mov_b32_e32 v1, v129
	v_lshl_add_u64 v[0:1], v[14:15], 0, v[0:1]
	global_store_dwordx2 v[0:1], v[48:49], off
	v_mul_f32_e32 v2, v52, v16
	v_mul_f32_e32 v3, v53, v16
	v_mul_f32_e32 v14, v55, v16
	s_waitcnt vmcnt(15)
	v_mul_f32_e32 v2, v150, v2
	v_mul_f32_e32 v3, v151, v3
	v_cvt_pk_bf16_f32 v2, v2, v3
	v_mul_f32_e32 v3, v54, v16
	v_mul_f32_e32 v3, v152, v3
	v_mul_f32_e32 v14, v153, v14
	v_cvt_pk_bf16_f32 v3, v3, v14
	global_store_dwordx2 v[0:1], v[2:3], off offset:16
	v_mul_f32_e32 v2, v56, v16
	v_mul_f32_e32 v3, v57, v16
	v_mul_f32_e32 v14, v59, v16
	s_waitcnt vmcnt(15)
	v_mul_f32_e32 v2, v154, v2
	v_mul_f32_e32 v3, v155, v3
	v_cvt_pk_bf16_f32 v2, v2, v3
	v_mul_f32_e32 v3, v58, v16
	v_mul_f32_e32 v3, v156, v3
	v_mul_f32_e32 v14, v157, v14
	v_cvt_pk_bf16_f32 v3, v3, v14
	global_store_dwordx2 v[0:1], v[2:3], off offset:32
	v_mul_f32_e32 v2, v60, v16
	v_mul_f32_e32 v3, v61, v16
	v_mul_f32_e32 v14, v63, v16
	s_waitcnt vmcnt(15)
	v_mul_f32_e32 v2, v2, v158
	v_mul_f32_e32 v3, v3, v159
	v_cvt_pk_bf16_f32 v2, v2, v3
	v_mul_f32_e32 v3, v62, v16
	v_mul_f32_e32 v3, v3, v160
	v_mul_f32_e32 v14, v14, v161
	v_cvt_pk_bf16_f32 v3, v3, v14
	global_store_dwordx2 v[0:1], v[2:3], off offset:48
	v_mul_f32_e32 v2, v69, v16
	v_mul_f32_e32 v3, v68, v16
	v_mul_f32_e32 v14, v34, v16
	s_waitcnt vmcnt(15)
	v_mul_f32_e32 v2, v2, v238
	v_mul_f32_e32 v3, v3, v239
	v_cvt_pk_bf16_f32 v2, v2, v3
	v_mul_f32_e32 v3, v70, v16
	v_mul_f32_e32 v3, v3, v240
	v_mul_f32_e32 v14, v14, v241
	v_cvt_pk_bf16_f32 v3, v3, v14
	global_store_dwordx2 v[0:1], v[2:3], off offset:64
	v_mul_f32_e32 v2, v36, v16
	v_mul_f32_e32 v3, v35, v16
	v_mul_f32_e32 v14, v37, v16
	s_waitcnt vmcnt(15)
	v_mul_f32_e32 v2, v2, v242
	v_mul_f32_e32 v3, v3, v243
	v_cvt_pk_bf16_f32 v2, v2, v3
	v_mul_f32_e32 v3, v38, v16
	v_mul_f32_e32 v3, v3, v244
	v_mul_f32_e32 v14, v14, v245
	v_cvt_pk_bf16_f32 v3, v3, v14
	global_store_dwordx2 v[0:1], v[2:3], off offset:80
	v_mul_f32_e32 v2, v33, v16
	v_mul_f32_e32 v3, v32, v16
	v_mul_f32_e32 v14, v39, v16
	s_waitcnt vmcnt(15)
	v_mul_f32_e32 v2, v2, v246
	v_mul_f32_e32 v3, v3, v247
	v_cvt_pk_bf16_f32 v2, v2, v3
	v_mul_f32_e32 v3, v40, v16
	v_mul_f32_e32 v3, v3, v248
	v_mul_f32_e32 v14, v14, v249
	v_cvt_pk_bf16_f32 v3, v3, v14
	global_store_dwordx2 v[0:1], v[2:3], off offset:96
	v_mul_f32_e32 v2, v42, v16
	v_mul_f32_e32 v3, v41, v16
	v_mul_f32_e32 v14, v44, v16
	s_waitcnt vmcnt(15)
	v_mul_f32_e32 v2, v2, v250
	v_mul_f32_e32 v3, v3, v251
	v_cvt_pk_bf16_f32 v2, v2, v3
	v_mul_f32_e32 v3, v46, v16
	v_mul_f32_e32 v3, v3, v252
	v_mul_f32_e32 v14, v14, v253
	v_cvt_pk_bf16_f32 v3, v3, v14
	global_store_dwordx2 v[0:1], v[2:3], off offset:112
	v_mul_f32_e32 v2, v45, v16
	v_mul_f32_e32 v3, v43, v16
	v_mul_f32_e32 v14, v18, v16
	s_waitcnt vmcnt(15)
	v_mul_f32_e32 v2, v2, v210
	v_mul_f32_e32 v3, v3, v211
	v_cvt_pk_bf16_f32 v2, v2, v3
	v_mul_f32_e32 v3, v47, v16
	v_mul_f32_e32 v3, v3, v212
	v_mul_f32_e32 v14, v14, v213
	v_cvt_pk_bf16_f32 v3, v3, v14
	global_store_dwordx2 v[0:1], v[2:3], off offset:128
	v_mul_f32_e32 v2, v20, v16
	v_mul_f32_e32 v3, v19, v16
	v_mul_f32_e32 v14, v23, v16
	s_waitcnt vmcnt(15)
	v_mul_f32_e32 v2, v2, v214
	v_mul_f32_e32 v3, v3, v215
	v_cvt_pk_bf16_f32 v2, v2, v3
	v_mul_f32_e32 v3, v72, v16
	v_mul_f32_e32 v3, v3, v216
	v_mul_f32_e32 v14, v14, v217
	v_cvt_pk_bf16_f32 v3, v3, v14
	global_store_dwordx2 v[0:1], v[2:3], off offset:144
	v_mul_f32_e32 v2, v22, v16
	v_mul_f32_e32 v3, v21, v16
	v_mul_f32_e32 v14, v24, v16
	s_waitcnt vmcnt(15)
	v_mul_f32_e32 v2, v2, v218
	v_mul_f32_e32 v3, v3, v219
	v_cvt_pk_bf16_f32 v2, v2, v3
	v_mul_f32_e32 v3, v25, v16
	v_mul_f32_e32 v3, v3, v220
	v_mul_f32_e32 v14, v14, v221
	v_cvt_pk_bf16_f32 v3, v3, v14
	global_store_dwordx2 v[0:1], v[2:3], off offset:160
	v_mul_f32_e32 v2, v27, v16
	v_mul_f32_e32 v3, v26, v16
	v_mul_f32_e32 v14, v30, v16
	s_waitcnt vmcnt(15)
	v_mul_f32_e32 v2, v2, v222
	v_mul_f32_e32 v3, v3, v223
	v_cvt_pk_bf16_f32 v2, v2, v3
	v_mul_f32_e32 v3, v73, v16
	v_mul_f32_e32 v3, v3, v224
	v_mul_f32_e32 v14, v14, v225
	v_cvt_pk_bf16_f32 v3, v3, v14
	global_store_dwordx2 v[0:1], v[2:3], off offset:176
	v_mul_f32_e32 v2, v29, v16
	v_mul_f32_e32 v3, v28, v16
	v_mul_f32_e32 v14, v31, v16
	s_waitcnt vmcnt(15)
	v_mul_f32_e32 v2, v2, v226
	v_mul_f32_e32 v3, v3, v227
	v_cvt_pk_bf16_f32 v2, v2, v3
	v_mul_f32_e32 v3, v74, v16
	v_mul_f32_e32 v3, v3, v228
	v_mul_f32_e32 v14, v14, v229
	v_cvt_pk_bf16_f32 v3, v3, v14
	global_store_dwordx2 v[0:1], v[2:3], off offset:192
	v_mul_f32_e32 v2, v76, v16
	v_mul_f32_e32 v3, v75, v16
	s_waitcnt vmcnt(15)
	v_mul_f32_e32 v2, v2, v230
	v_mul_f32_e32 v3, v3, v231
	v_cvt_pk_bf16_f32 v2, v2, v3
	v_mul_f32_e32 v3, v6, v16
	v_mul_f32_e32 v3, v3, v232
	v_mul_f32_e32 v6, v7, v16
	v_mul_f32_e32 v6, v6, v233
	v_cvt_pk_bf16_f32 v3, v3, v6
	global_store_dwordx2 v[0:1], v[2:3], off offset:208
	v_mul_f32_e32 v2, v4, v16
	v_mul_f32_e32 v3, v5, v16
	v_mul_f32_e32 v4, v9, v16
	v_mul_f32_e32 v6, v10, v16
	s_waitcnt vmcnt(15)
	v_mul_f32_e32 v2, v2, v234
	v_mul_f32_e32 v3, v3, v235
	v_cvt_pk_bf16_f32 v2, v2, v3
	v_mul_f32_e32 v3, v8, v16
	v_mul_f32_e32 v3, v3, v236
	v_mul_f32_e32 v4, v4, v237
	v_cvt_pk_bf16_f32 v3, v3, v4
	global_store_dwordx2 v[0:1], v[2:3], off offset:224
	s_waitcnt vmcnt(15)
	v_mul_f32_e32 v2, v6, v184
	v_mul_f32_e32 v6, v11, v16
	v_mul_f32_e32 v3, v6, v185
	v_cvt_pk_bf16_f32 v2, v2, v3
	v_mul_f32_e32 v3, v12, v16
	v_mul_f32_e32 v3, v3, v186
	v_mul_f32_e32 v4, v13, v16
	v_mul_f32_e32 v4, v4, v187
	v_cvt_pk_bf16_f32 v3, v3, v4
	global_store_dwordx2 v[0:1], v[2:3], off offset:240
	s_branch .LBB0_204
